# norm1: second row's gain/scale/shift loads issued in the same batch as the first row's
# baseline (speedup 1.0000x reference)
.LBB0_776:
	s_or_b64 exec, exec, s[0:1]
	v_min_i32_e32 v50, 0x8000, v32
	v_ashrrev_i32_e32 v50, 12, v50
	v_mul_i32_i24_e32 v50, 9, v50
	v_ashrrev_i32_e32 v51, 31, v50
	v_lshlrev_b64 v[50:51], 12, v[50:51]
	v_lshl_add_u64 v[80:81], v[40:41], 0, v[50:51]
	s_mov_b64 s[0:1], 0x1000
	v_lshl_add_u64 v[82:83], v[80:81], 0, s[0:1]
	s_movk_i32 s0, 0x1000
	v_add_co_u32_e32 v68, vcc, s0, v80
	global_load_dwordx4 v[50:53], v[38:39], off offset:16
	global_load_dwordx4 v[54:57], v[38:39], off
	flat_load_dwordx4 v[64:67], v[82:83] offset:16
	v_addc_co_u32_e32 v69, vcc, 0, v81, vcc
	flat_load_dwordx4 v[68:71], v[68:69]
	s_nop 0
	flat_load_dwordx4 v[72:75], v[80:81] offset:16
	flat_load_dwordx4 v[76:79], v[80:81]
	global_load_dwordx4 v[112:115], v[38:39], off offset:2048
	global_load_dwordx4 v[116:119], v[82:83], off offset:2048
	global_load_dwordx4 v[120:123], v[38:39], off offset:2064
	global_load_dwordx4 v[124:127], v[82:83], off offset:2064
	global_load_dwordx4 v[128:131], v[80:81], off offset:2048
	global_load_dwordx4 v[132:135], v[80:81], off offset:2064
	v_min_i32_e32 v104, 0x8000, v33
	v_ashrrev_i32_e32 v104, 12, v104
	v_mul_i32_i24_e32 v104, 9, v104
	v_ashrrev_i32_e32 v105, 31, v104
	v_lshlrev_b64 v[104:105], 12, v[104:105]
	v_lshl_add_u64 v[104:105], v[40:41], 0, v[104:105]
	s_mov_b64 s[98:99], 0x1000
	v_lshl_add_u64 v[106:107], v[104:105], 0, s[98:99]
	global_load_dwordx4 v[224:227], v[38:39], off offset:16
	global_load_dwordx4 v[228:231], v[38:39], off
	global_load_dwordx4 v[232:235], v[106:107], off offset:16
	global_load_dwordx4 v[236:239], v[106:107], off
	global_load_dwordx4 v[240:243], v[104:105], off offset:16
	global_load_dwordx4 v[244:247], v[104:105], off
	global_load_dwordx4 v[144:147], v[38:39], off offset:2048
	global_load_dwordx4 v[148:151], v[106:107], off offset:2048
	global_load_dwordx4 v[152:155], v[38:39], off offset:2064
	global_load_dwordx4 v[156:159], v[106:107], off offset:2064
	global_load_dwordx4 v[160:163], v[104:105], off offset:2048
	global_load_dwordx4 v[164:167], v[104:105], off offset:2064
	s_waitcnt vmcnt(0) lgkmcnt(0)
	v_mul_f32_e32 v63, v17, v17
	v_mul_f32_e32 v84, v25, v25
	v_fmac_f32_e32 v63, v16, v16
	v_fmac_f32_e32 v84, v24, v24
	v_fmac_f32_e32 v63, v18, v18
	v_fmac_f32_e32 v84, v26, v26
	v_fmac_f32_e32 v63, v19, v19
	v_fmac_f32_e32 v84, v27, v27
	v_add_f32_e32 v63, v84, v63
	v_mul_f32_e32 v84, v13, v13
	v_fmac_f32_e32 v84, v12, v12
	v_fmac_f32_e32 v84, v14, v14
	v_fmac_f32_e32 v84, v15, v15
	v_add_f32_e32 v63, v84, v63
	v_mul_f32_e32 v84, v29, v29
	v_fmac_f32_e32 v84, v28, v28
	v_fmac_f32_e32 v84, v30, v30
	v_fmac_f32_e32 v84, v31, v31
	v_add_f32_e32 v63, v84, v63
	ds_bpermute_b32 v84, v35, v63
	s_mov_b32 s0, 0x800000
	s_waitcnt lgkmcnt(0)
	v_add_f32_e32 v63, v63, v84
	ds_bpermute_b32 v84, v58, v63
	s_waitcnt lgkmcnt(0)
	v_add_f32_e32 v63, v63, v84
	ds_bpermute_b32 v84, v59, v63
	s_waitcnt lgkmcnt(0)
	v_add_f32_e32 v63, v63, v84
	ds_bpermute_b32 v84, v60, v63
	s_waitcnt lgkmcnt(0)
	v_add_f32_e32 v63, v63, v84
	ds_bpermute_b32 v84, v61, v63
	s_waitcnt lgkmcnt(0)
	v_add_f32_e32 v63, v63, v84
	ds_bpermute_b32 v86, v62, v63
	v_lshl_add_u64 v[84:85], v[46:47], 0, v[42:43]
	s_waitcnt lgkmcnt(0)
	v_add_f32_e32 v63, v63, v86
	v_fmamk_f32 v63, v63, 0x3a800000, v191
	v_mul_f32_e32 v86, 0x4b800000, v63
	v_cmp_gt_f32_e32 vcc, s0, v63
	s_mov_b32 s0, 0xc944000
	v_add_co_u32_e64 v84, s[0:1], s0, v84
	v_cndmask_b32_e32 v63, v63, v86, vcc
	v_rsq_f32_e32 v63, v63
	v_addc_co_u32_e64 v85, s[0:1], 0, v85, s[0:1]
	s_mov_b32 s0, 0x8800
	v_mul_f32_e32 v86, 0x45800000, v63
	v_cndmask_b32_e32 v86, v63, v86, vcc
	v_pk_mul_f32 v[18:19], v[18:19], v[86:87] op_sel_hi:[1,0]
	v_pk_mul_f32 v[16:17], v[16:17], v[86:87] op_sel_hi:[1,0]
	v_pk_mul_f32 v[26:27], v[26:27], v[86:87] op_sel_hi:[1,0]
	v_pk_mul_f32 v[24:25], v[24:25], v[86:87] op_sel_hi:[1,0]
	v_pk_mul_f32 v[14:15], v[14:15], v[86:87] op_sel_hi:[1,0]
	v_pk_mul_f32 v[12:13], v[12:13], v[86:87] op_sel_hi:[1,0]
	v_pk_mul_f32 v[24:25], v[50:51], v[24:25]
	v_pk_mul_f32 v[16:17], v[54:55], v[16:17]
	v_pk_mul_f32 v[18:19], v[56:57], v[18:19]
	v_pk_mul_f32 v[26:27], v[52:53], v[26:27]
	v_pk_add_f32 v[50:51], v[66:67], 1.0 op_sel_hi:[1,0]
	v_pk_add_f32 v[52:53], v[64:65], 1.0 op_sel_hi:[1,0]
	v_pk_add_f32 v[54:55], v[70:71], 1.0 op_sel_hi:[1,0]
	v_pk_add_f32 v[56:57], v[68:69], 1.0 op_sel_hi:[1,0]
	v_pk_fma_f32 v[26:27], v[50:51], v[26:27], v[74:75]
	v_pk_fma_f32 v[24:25], v[52:53], v[24:25], v[72:73]
	v_pk_fma_f32 v[50:51], v[54:55], v[18:19], v[78:79]
	v_pk_fma_f32 v[16:17], v[56:57], v[16:17], v[76:77]
	v_cvt_pk_bf16_f32 v18, v24, v25
	v_cvt_pk_bf16_f32 v19, v26, v27
	v_cvt_pk_bf16_f32 v16, v16, v17
	v_cvt_pk_bf16_f32 v17, v50, v51
	flat_store_dwordx4 v[84:85], v[16:19]
	s_nop 1
	v_mov_b64_e32 v[24:25], v[112:113]
	v_mov_b64_e32 v[26:27], v[114:115]
	s_nop 1
	v_mov_b64_e32 v[50:51], v[116:117]
	v_mov_b64_e32 v[52:53], v[118:119]
	s_nop 1
	v_mov_b64_e32 v[54:55], v[120:121]
	v_mov_b64_e32 v[56:57], v[122:123]
	s_nop 1
	v_mov_b64_e32 v[64:65], v[124:125]
	v_mov_b64_e32 v[66:67], v[126:127]
	s_nop 1
	v_mov_b64_e32 v[68:69], v[128:129]
	v_mov_b64_e32 v[70:71], v[130:131]
	s_nop 1
	v_mov_b64_e32 v[72:73], v[132:133]
	v_mov_b64_e32 v[74:75], v[134:135]
	v_mul_f32_e32 v16, v5, v5
	v_mul_f32_e32 v17, v9, v9
	v_mul_f32_e32 v18, v1, v1
	v_fmac_f32_e32 v16, v4, v4
	v_fmac_f32_e32 v17, v8, v8
	v_mul_f32_e32 v19, v21, v21
	v_fmac_f32_e32 v18, v0, v0
	v_fmac_f32_e32 v16, v6, v6
	v_fmac_f32_e32 v17, v10, v10
	v_fmac_f32_e32 v19, v20, v20
	v_fmac_f32_e32 v18, v2, v2
	v_fmac_f32_e32 v16, v7, v7
	v_fmac_f32_e32 v17, v11, v11
	v_fmac_f32_e32 v19, v22, v22
	v_fmac_f32_e32 v18, v3, v3
	v_add_f32_e32 v16, v17, v16
	v_fmac_f32_e32 v19, v23, v23
	v_add_f32_e32 v16, v18, v16
	v_add_f32_e32 v16, v19, v16
	ds_bpermute_b32 v17, v35, v16
	v_pk_mul_f32 v[18:19], v[30:31], v[86:87] op_sel_hi:[1,0]
	v_pk_mul_f32 v[28:29], v[28:29], v[86:87] op_sel_hi:[1,0]
	v_cmp_gt_i32_e32 vcc, s0, v33
	s_waitcnt lgkmcnt(0)
	v_add_f32_e32 v16, v16, v17
	ds_bpermute_b32 v17, v58, v16
	s_waitcnt lgkmcnt(0)
	v_add_f32_e32 v16, v16, v17
	ds_bpermute_b32 v17, v59, v16
	s_waitcnt lgkmcnt(0)
	v_add_f32_e32 v16, v16, v17
	ds_bpermute_b32 v17, v60, v16
	s_waitcnt lgkmcnt(0)
	v_add_f32_e32 v16, v16, v17
	ds_bpermute_b32 v17, v61, v16
	s_waitcnt lgkmcnt(0)
	v_add_f32_e32 v16, v16, v17
	ds_bpermute_b32 v17, v62, v16
	s_waitcnt vmcnt(0)
	v_pk_mul_f32 v[12:13], v[24:25], v[12:13]
	v_pk_mul_f32 v[14:15], v[26:27], v[14:15]
	v_pk_add_f32 v[24:25], v[52:53], 1.0 op_sel_hi:[1,0]
	v_pk_add_f32 v[26:27], v[50:51], 1.0 op_sel_hi:[1,0]
	v_pk_mul_f32 v[28:29], v[54:55], v[28:29]
	v_pk_mul_f32 v[18:19], v[56:57], v[18:19]
	v_pk_add_f32 v[30:31], v[66:67], 1.0 op_sel_hi:[1,0]
	v_pk_add_f32 v[50:51], v[64:65], 1.0 op_sel_hi:[1,0]
	v_pk_fma_f32 v[14:15], v[24:25], v[14:15], v[70:71]
	v_pk_fma_f32 v[12:13], v[26:27], v[12:13], v[68:69]
	v_pk_fma_f32 v[18:19], v[18:19], v[30:31], v[74:75]
	v_pk_fma_f32 v[24:25], v[28:29], v[50:51], v[72:73]
	v_cvt_pk_bf16_f32 v12, v12, v13
	v_cvt_pk_bf16_f32 v13, v14, v15
	v_cvt_pk_bf16_f32 v14, v24, v25
	v_cvt_pk_bf16_f32 v15, v18, v19
	flat_store_dwordx4 v[84:85], v[12:15] offset:1024
	s_and_saveexec_b64 s[48:49], vcc
	s_cbranch_execz .LBB0_771
	v_min_i32_e32 v12, 0x8000, v33
	v_ashrrev_i32_e32 v12, 12, v12
	v_mul_i32_i24_e32 v12, 9, v12
	v_ashrrev_i32_e32 v13, 31, v12
	v_lshlrev_b64 v[12:13], 12, v[12:13]
	v_lshl_add_u64 v[68:69], v[40:41], 0, v[12:13]
	s_mov_b64 s[0:1], 0x1000
	v_lshl_add_u64 v[18:19], v[68:69], 0, s[0:1]
	s_movk_i32 s0, 0x1000
	v_add_co_u32_e32 v50, vcc, s0, v68
	v_mov_b64_e32 v[12:13], v[224:225]
	v_mov_b64_e32 v[14:15], v[226:227]
	v_mov_b64_e32 v[24:25], v[228:229]
	v_mov_b64_e32 v[26:27], v[230:231]
	v_mov_b64_e32 v[28:29], v[232:233]
	v_mov_b64_e32 v[30:31], v[234:235]
	v_addc_co_u32_e32 v51, vcc, 0, v69, vcc
	v_mov_b64_e32 v[50:51], v[236:237]
	v_mov_b64_e32 v[52:53], v[238:239]
	s_nop 0
	v_mov_b64_e32 v[54:55], v[240:241]
	v_mov_b64_e32 v[56:57], v[242:243]
	v_mov_b64_e32 v[64:65], v[244:245]
	v_mov_b64_e32 v[66:67], v[246:247]
	s_waitcnt lgkmcnt(0)
	v_add_f32_e32 v33, v16, v17
	v_fmamk_f32 v33, v33, 0x3a800000, v191
	s_mov_b32 s0, 0x800000
	v_mul_f32_e32 v63, 0x4b800000, v33
	v_cmp_gt_f32_e32 vcc, s0, v33
	v_lshl_add_u64 v[16:17], v[44:45], 0, v[42:43]
	s_mov_b32 s0, 0xc944000
	v_cndmask_b32_e32 v33, v33, v63, vcc
	v_rsq_f32_e32 v33, v33
	v_add_co_u32_e64 v70, s[0:1], s0, v16
	v_mul_f32_e32 v16, 0x45800000, v33
	v_cndmask_b32_e32 v72, v33, v16, vcc
	v_pk_mul_f32 v[6:7], v[6:7], v[72:73] op_sel_hi:[1,0]
	v_pk_mul_f32 v[4:5], v[4:5], v[72:73] op_sel_hi:[1,0]
	v_pk_mul_f32 v[10:11], v[10:11], v[72:73] op_sel_hi:[1,0]
	v_pk_mul_f32 v[8:9], v[8:9], v[72:73] op_sel_hi:[1,0]
	v_addc_co_u32_e64 v71, s[0:1], 0, v17, s[0:1]
	v_pk_mul_f32 v[2:3], v[2:3], v[72:73] op_sel_hi:[1,0]
	v_pk_mul_f32 v[0:1], v[0:1], v[72:73] op_sel_hi:[1,0]
	v_pk_mul_f32 v[22:23], v[22:23], v[72:73] op_sel_hi:[1,0]
	v_pk_mul_f32 v[20:21], v[20:21], v[72:73] op_sel_hi:[1,0]
	s_waitcnt vmcnt(0)
	v_pk_mul_f32 v[8:9], v[8:9], v[12:13]
	v_pk_mul_f32 v[4:5], v[4:5], v[24:25]
	v_pk_mul_f32 v[6:7], v[6:7], v[26:27]
	v_pk_mul_f32 v[10:11], v[10:11], v[14:15]
	v_pk_add_f32 v[12:13], v[30:31], 1.0 op_sel_hi:[1,0]
	v_pk_add_f32 v[14:15], v[28:29], 1.0 op_sel_hi:[1,0]
	v_pk_add_f32 v[16:17], v[52:53], 1.0 op_sel_hi:[1,0]
	v_pk_add_f32 v[24:25], v[50:51], 1.0 op_sel_hi:[1,0]
	v_pk_fma_f32 v[10:11], v[10:11], v[12:13], v[56:57]
	v_pk_fma_f32 v[8:9], v[8:9], v[14:15], v[54:55]
	v_pk_fma_f32 v[12:13], v[6:7], v[16:17], v[66:67]
	v_pk_fma_f32 v[4:5], v[4:5], v[24:25], v[64:65]
	v_cvt_pk_bf16_f32 v6, v8, v9
	v_cvt_pk_bf16_f32 v7, v10, v11
	v_cvt_pk_bf16_f32 v4, v4, v5
	v_cvt_pk_bf16_f32 v5, v12, v13
	flat_store_dwordx4 v[70:71], v[4:7]
	s_nop 1
	v_mov_b64_e32 v[4:5], v[144:145]
	v_mov_b64_e32 v[6:7], v[146:147]
	s_nop 0
	s_nop 1
	v_mov_b64_e32 v[8:9], v[148:149]
	v_mov_b64_e32 v[10:11], v[150:151]
	s_nop 1
	v_mov_b64_e32 v[12:13], v[152:153]
	v_mov_b64_e32 v[14:15], v[154:155]
	s_nop 0
	s_nop 1
	v_mov_b64_e32 v[16:17], v[156:157]
	v_mov_b64_e32 v[18:19], v[158:159]
	s_nop 0
	s_nop 1
	v_mov_b64_e32 v[24:25], v[160:161]
	v_mov_b64_e32 v[26:27], v[162:163]
	s_nop 1
	v_mov_b64_e32 v[28:29], v[164:165]
	v_mov_b64_e32 v[30:31], v[166:167]
	s_waitcnt vmcnt(0)
	v_pk_mul_f32 v[0:1], v[0:1], v[4:5]
	v_pk_mul_f32 v[2:3], v[2:3], v[6:7]
	s_waitcnt lgkmcnt(0)
	v_pk_add_f32 v[4:5], v[10:11], 1.0 op_sel_hi:[1,0]
	v_pk_add_f32 v[6:7], v[8:9], 1.0 op_sel_hi:[1,0]
	v_pk_mul_f32 v[8:9], v[20:21], v[12:13]
	v_pk_mul_f32 v[10:11], v[22:23], v[14:15]
	v_pk_add_f32 v[12:13], v[18:19], 1.0 op_sel_hi:[1,0]
	v_pk_add_f32 v[14:15], v[16:17], 1.0 op_sel_hi:[1,0]
	v_pk_fma_f32 v[2:3], v[2:3], v[4:5], v[26:27]
	v_pk_fma_f32 v[0:1], v[0:1], v[6:7], v[24:25]
	v_pk_fma_f32 v[4:5], v[10:11], v[12:13], v[30:31]
	v_pk_fma_f32 v[6:7], v[8:9], v[14:15], v[28:29]
	v_cvt_pk_bf16_f32 v0, v0, v1
	v_cvt_pk_bf16_f32 v1, v2, v3
	v_cvt_pk_bf16_f32 v2, v6, v7
	v_cvt_pk_bf16_f32 v3, v4, v5
	flat_store_dwordx4 v[70:71], v[0:3] offset:1024
	s_branch .LBB0_771
